# baseline (speedup 1.0000x reference)
; __global__ void __launch_bounds__(NTHREADS) fwd_megakernel(Params p_unused) {
;     ...
;   for (int li = 0; li < 2; ++li) {
;     const int l = 1 - li;
;     if (l == 0) {
;       CParamsPtr k = fresh_params();
;       convert_x(k->x, (bf16_t*)(k->ws + WS_XB), (size_t)MTOK * DM);
;     }
;     {
;       CParamsPtr k = fresh_params();
;       transpose_convert_wide(k->w_out + (size_t)l * DM * DM, (bf16_t*)(k->ws + WS_WOUTT) + (size_t)l * DM * DM, DM, DM, DM);
;     }
;     {
;       CParamsPtr k = fresh_params();
;       const int split = (l == 1 && (GEMM1_TILES % (int)gridDim.x) != 0) ? WIN_SPLIT_TILES : 0;
;       transpose_convert_wide(k->w_in + (size_t)l * DM * NIN, (bf16_t*)(k->ws + WS_WINT) + (size_t)l * NPAD * DM, DM, NIN,
;                              NPAD, split);
;     }
.LBB0_20:
	s_or_b64 exec, exec, s[6:7]
	s_mov_b32 s13, 0
	s_mov_b32 s3, s13
	s_mov_b32 s19, s13
	s_lshl_b64 s[14:15], s[2:3], 12
	s_lshl_b64 s[16:17], s[18:19], 12
	s_cmpk_lt_i32 s2, 0x400
	s_cselect_b64 s[6:7], -1, 0
	s_cmpk_lt_i32 s2, 0x80
	s_cselect_b64 s[24:25], -1, 0
	s_cmp_lt_i32 s2, 4
	s_cselect_b64 s[26:27], -1, 0
	s_abs_i32 s8, s18
	v_cvt_f32_u32_e32 v1, s8
	s_sub_i32 s9, 0, s8
	v_mov_b32_e32 v35, 0
	s_waitcnt lgkmcnt(0)
	v_rcp_iflag_f32_e32 v1, v1
	s_barrier
	ds_read_b96 v[2:4], v35
	v_mul_f32_e32 v1, 0x4f7ffffe, v1
	v_cvt_u32_f32_e32 v1, v1
	s_mov_b64 s[38:39], -1
	s_mov_b64 s[36:37], 0x2000000
	s_waitcnt lgkmcnt(0)
	v_readfirstlane_b32 s84, v2
	v_readfirstlane_b32 s12, v1
	s_mul_i32 s9, s9, s12
	s_mul_hi_u32 s9, s12, s9
	s_add_i32 s12, s12, s9
	s_mul_hi_u32 s9, s12, 0x7a0
	s_mul_i32 s9, s9, s8
	s_sub_i32 s9, 0x7a0, s9
	s_sub_i32 s12, s9, s8
	s_cmp_ge_u32 s9, s8
	s_cselect_b32 s9, s12, s9
	s_sub_i32 s12, s9, s8
	s_cmp_ge_u32 s9, s8
	s_cselect_b32 s8, s12, s9
	s_cmp_eq_u32 s8, 0
	s_cselect_b32 s56, 0, 0x840
	s_lshl_b64 s[28:29], s[2:3], 14
	s_or_b32 s28, s28, 16
	s_lshl_b64 s[30:31], s[18:19], 14
	s_lshl_b64 s[8:9], s[2:3], 13
	s_add_u32 s57, s8, 0x13400000
	v_cndmask_b32_e64 v1, 0, 1, s[6:7]
	v_readfirstlane_b32 s70, v3
	v_readfirstlane_b32 s33, v4
	s_addc_u32 s58, s9, 0
	s_lshl_b64 s[34:35], s[18:19], 13
	s_lshl_b32 s19, s2, 8
	s_lshl_b32 s3, s2, 6
	s_mov_b32 s12, 1
	s_mov_b64 s[8:9], 0
	s_mov_b64 s[40:41], 0x1ffffff
	v_cmp_ne_u32_e64 s[6:7], 1, v1
	s_movk_i32 s59, 0x404
	s_mov_b64 s[42:43], 0xf400000
	s_movk_i32 s60, 0x1000
	s_movk_i32 s61, 0x3c30
	s_mov_b32 s62, 0xf0c0
	s_movk_i32 s63, 0x104
	s_lshl_b32 s64, s18, 8
	s_branch .LBB0_22

;     ...
;     __syncthreads();
; #pragma unroll
;     for (int i = 0; i < 8; ++i) {
;       const int id = tid + i * 512;
;       const int r = id >> 6, c4 = (id & 63) * 4;
;       tile[r * 257 + c4 + 0] = v[i][0];
;       tile[r * 257 + c4 + 1] = v[i][1];
;       tile[r * 257 + c4 + 2] = v[i][2];
;       tile[r * 257 + c4 + 3] = v[i][3];
;     }
;     __syncthreads();
; #pragma unroll
;     for (int i = 0; i < 4; ++i) {
;       const int id = tid + i * 512;
;       const int n = id >> 3, kc = id & 7;
;       uint4 o;
;       o.x = pack2(tile[(kc * 8 + 0) * 257 + n], tile[(kc * 8 + 1) * 257 + n]);
;       o.y = pack2(tile[(kc * 8 + 2) * 257 + n], tile[(kc * 8 + 3) * 257 + n]);
;       o.z = pack2(tile[(kc * 8 + 4) * 257 + n], tile[(kc * 8 + 5) * 257 + n]);
;       o.w = pack2(tile[(kc * 8 + 6) * 257 + n], tile[(kc * 8 + 7) * 257 + n]);
;       *(uint4*)(dst + (size_t)(n0 + n) * K + k0 + kc * 8) = o;
;     }
; template <int l>
; __device__ __forceinline__ void layer_body(const XcdBarrier& xb) {
;     ...
;     if (l == 0) {
;       const int busy = GEMM1_TILES % (int)gridDim.x;
;       if (busy != 0 && (int)blockIdx.x >= busy) {
;         CParamsPtr k = fresh_params();
;         transpose_convert_wide(k->w_in + (size_t)DM * NIN, (bf16_t*)(k->ws + WS_WINT) + (size_t)NPAD * DM, DM, NIN, NPAD, 0,
;                                WIN_SPLIT_TILES, (int)blockIdx.x - busy, (int)gridDim.x - busy);
;       }
.LBB0_139:
	s_load_dword s8, s[10:11], 0x10
	s_load_dword s24, s[10:11], 0x0
	s_waitcnt lgkmcnt(0)
	s_lshr_b32 s8, s8, 16
	s_cmp_lg_u32 s8, 0
	s_cselect_b64 s[8:9], -1, 0
	s_cmp_lg_u64 s[8:9], 0
	s_addc_u32 s68, s24, 0
	v_cndmask_b32_e64 v0, 0, 1, s[8:9]
	s_abs_i32 s8, s68
	v_cvt_f32_u32_e32 v1, s8
	s_sub_i32 s9, 0, s8
	v_readfirstlane_b32 s25, v0
	v_rcp_iflag_f32_e32 v1, v1
	s_nop 0
	v_mul_f32_e32 v1, 0x4f7ffffe, v1
	v_cvt_u32_f32_e32 v1, v1
	s_nop 0
	v_readfirstlane_b32 s10, v1
	s_mul_i32 s9, s9, s10
	s_mul_hi_u32 s9, s10, s9
	s_add_i32 s10, s10, s9
	s_mul_hi_u32 s9, s10, 0x7a0
	s_mul_i32 s9, s9, s8
	s_sub_i32 s9, 0x7a0, s9
	s_sub_i32 s10, s9, s8
	s_cmp_ge_u32 s9, s8
	s_cselect_b32 s9, s10, s9
	s_sub_i32 s10, s9, s8
	s_cmp_ge_u32 s9, s8
	s_cselect_b32 s10, s10, s9
	s_cmp_eq_u32 s10, 0
	s_cselect_b64 s[8:9], -1, 0
	s_cmp_lt_i32 s2, s10
	s_cselect_b64 s[12:13], -1, 0
	s_or_b64 s[8:9], s[8:9], s[12:13]
	s_and_b64 vcc, exec, s[8:9]
	s_cbranch_vccnz .LBB0_159
	s_sub_i32 s14, s2, s10
	s_mov_b64 s[8:9], s[0:1]
	v_mov_b32_e32 v0, v254
	s_cmpk_gt_i32 s14, 0x83f
	s_cbranch_scc1 .LBB0_159
	s_load_dwordx2 s[12:13], s[8:9], 0x8
	s_load_dwordx2 s[16:17], s[8:9], 0x68
	v_lshlrev_b32_e32 v1, 2, v0
	v_and_b32_e32 v38, 0xfc, v1
	v_lshlrev_b32_e32 v2, 2, v38
	v_mov_b32_e32 v3, 0
	s_waitcnt lgkmcnt(0)
	v_lshl_add_u64 v[4:5], s[12:13], 0, v[2:3]
	v_add_u32_e32 v1, 16, v2
	v_lshlrev_b32_e32 v2, 3, v0
	s_sub_i32 s15, s68, s10
	s_mov_b64 s[8:9], 0xf0c0000
	v_and_b32_e32 v2, 56, v2
	s_movk_i32 s10, 0x404
	v_lshl_add_u64 v[32:33], v[4:5], 0, s[8:9]
	v_mad_u32_u24 v4, v2, s10, 16
	v_lshlrev_b32_e32 v2, 1, v2
	v_add_u32_e32 v6, 0x800, v0
	v_lshl_add_u64 v[2:3], s[16:17], 0, v[2:3]
	s_mov_b64 s[8:9], 0x7a00000
	v_ashrrev_i32_e32 v45, 6, v6
	v_add_u32_e32 v6, 0xa00, v0
	v_lshl_add_u64 v[34:35], v[2:3], 0, s[8:9]
	v_ashrrev_i32_e32 v39, 3, v0
	v_ashrrev_i32_e32 v41, 6, v0
	v_add_u32_e32 v2, 0x200, v0
	v_add_u32_e32 v3, 0x400, v0
	v_add_u32_e32 v5, 0x600, v0
	v_ashrrev_i32_e32 v46, 6, v6
	v_add_u32_e32 v6, 0xc00, v0
	v_add_u32_e32 v0, 0xe00, v0
	v_ashrrev_i32_e32 v42, 6, v2
	v_ashrrev_i32_e32 v43, 6, v3
	v_ashrrev_i32_e32 v44, 6, v5
	v_ashrrev_i32_e32 v47, 6, v6
	v_ashrrev_i32_e32 v48, 6, v0
	v_mul_lo_u32 v0, v41, s10
	v_mul_lo_u32 v6, v42, s10
	v_mul_lo_u32 v7, v43, s10
	v_mul_lo_u32 v8, v44, s10
	v_mul_lo_u32 v9, v45, s10
	v_mul_lo_u32 v10, v46, s10
	v_mul_lo_u32 v11, v47, s10
	v_ashrrev_i32_e32 v49, 3, v2
	v_ashrrev_i32_e32 v51, 3, v3
	v_ashrrev_i32_e32 v53, 3, v5
	v_mul_lo_u32 v2, v48, s10
	v_lshl_add_u32 v40, v39, 2, v4
	v_lshl_add_u32 v50, v49, 2, v4
	v_lshl_add_u32 v52, v51, 2, v4
	v_lshl_add_u32 v54, v53, 2, v4
	s_lshl_b32 s16, s14, 8
	s_lshl_b32 s17, s15, 8
	s_movk_i32 s19, 0x3c30
	s_mov_b32 s26, 0xf0c0
	v_add_u32_e32 v55, v1, v0
	v_add_u32_e32 v56, v1, v6
	v_add_u32_e32 v57, v1, v7
	v_add_u32_e32 v58, v1, v8
	v_add_u32_e32 v59, v1, v9
	v_add_u32_e32 v60, v1, v10
	v_add_u32_e32 v61, v1, v11
	v_add_u32_e32 v62, v1, v2
	s_branch .LBB0_143
.LBB0_142:
	s_or_b64 exec, exec, s[12:13]
	s_barrier
	s_waitcnt vmcnt(7)
	ds_write2_b32 v55, v0, v1 offset1:1
	ds_write2_b32 v55, v2, v3 offset0:2 offset1:3
	s_waitcnt vmcnt(6)
	ds_write2_b32 v56, v8, v9 offset1:1
	ds_write2_b32 v56, v10, v11 offset0:2 offset1:3
	s_waitcnt vmcnt(5)
	ds_write2_b32 v57, v4, v5 offset1:1
	ds_write2_b32 v57, v6, v7 offset0:2 offset1:3
	s_waitcnt vmcnt(4)
	ds_write2_b32 v58, v16, v17 offset1:1
	ds_write2_b32 v58, v18, v19 offset0:2 offset1:3
	s_waitcnt vmcnt(3)
	ds_write2_b32 v59, v12, v13 offset1:1
	ds_write2_b32 v59, v14, v15 offset0:2 offset1:3
	s_waitcnt vmcnt(2)
	ds_write2_b32 v60, v24, v25 offset1:1
	ds_write2_b32 v60, v26, v27 offset0:2 offset1:3
	s_waitcnt vmcnt(1)
	ds_write2_b32 v61, v20, v21 offset1:1
	ds_write2_b32 v61, v22, v23 offset0:2 offset1:3
	s_waitcnt vmcnt(0)
	ds_write2_b32 v62, v28, v29 offset1:1
	ds_write2_b32 v62, v30, v31 offset0:2 offset1:3
	s_waitcnt lgkmcnt(0)
	s_barrier
	ds_read_b32 v0, v40
	ds_read_b32 v1, v40 offset:1028
	ds_read_b32 v2, v40 offset:2056
	ds_read_b32 v3, v40 offset:3084
	ds_read_b32 v6, v40 offset:4112
	ds_read_b32 v7, v40 offset:5140
	ds_read_b32 v8, v40 offset:6168
	ds_read_b32 v9, v40 offset:7196
	s_waitcnt lgkmcnt(6)
	v_cvt_pk_bf16_f32 v0, v0, v1
	s_waitcnt lgkmcnt(4)
	v_cvt_pk_bf16_f32 v1, v2, v3
	s_waitcnt lgkmcnt(2)
	v_cvt_pk_bf16_f32 v2, v6, v7
	v_add_u32_e32 v6, s8, v39
	s_waitcnt lgkmcnt(0)
	v_cvt_pk_bf16_f32 v3, v8, v9
	ds_read_b32 v8, v50
	ds_read_b32 v9, v50 offset:1028
	ds_read_b32 v10, v50 offset:2056
	ds_read_b32 v11, v50 offset:3084
	ds_read_b32 v12, v50 offset:4112
	ds_read_b32 v13, v50 offset:5140
	ds_read_b32 v14, v50 offset:6168
	ds_read_b32 v15, v50 offset:7196
	s_ashr_i32 s11, s10, 31
	v_ashrrev_i32_e32 v7, 31, v6
	v_lshl_add_u64 v[4:5], s[10:11], 1, v[34:35]
	v_lshlrev_b64 v[6:7], 13, v[6:7]
	v_lshl_add_u64 v[6:7], v[4:5], 0, v[6:7]
	global_store_dwordx4 v[6:7], v[0:3], off
	v_add_u32_e32 v6, s8, v49
	v_ashrrev_i32_e32 v7, 31, v6
	s_waitcnt lgkmcnt(6)
	v_cvt_pk_bf16_f32 v0, v8, v9
	s_waitcnt lgkmcnt(4)
	v_cvt_pk_bf16_f32 v1, v10, v11
	s_waitcnt lgkmcnt(2)
	v_cvt_pk_bf16_f32 v2, v12, v13
	s_waitcnt lgkmcnt(0)
	v_cvt_pk_bf16_f32 v3, v14, v15
	ds_read_b32 v8, v52
	ds_read_b32 v9, v52 offset:1028
	ds_read_b32 v10, v52 offset:2056
	ds_read_b32 v11, v52 offset:3084
	ds_read_b32 v12, v52 offset:4112
	ds_read_b32 v13, v52 offset:5140
	ds_read_b32 v14, v52 offset:6168
	ds_read_b32 v15, v52 offset:7196
	v_lshlrev_b64 v[6:7], 13, v[6:7]
	v_lshl_add_u64 v[6:7], v[4:5], 0, v[6:7]
	global_store_dwordx4 v[6:7], v[0:3], off
	v_add_u32_e32 v6, s8, v51
	v_ashrrev_i32_e32 v7, 31, v6
	s_waitcnt lgkmcnt(6)
	v_cvt_pk_bf16_f32 v0, v8, v9
	s_waitcnt lgkmcnt(4)
	v_cvt_pk_bf16_f32 v1, v10, v11
	s_waitcnt lgkmcnt(2)
	v_cvt_pk_bf16_f32 v2, v12, v13
	s_waitcnt lgkmcnt(0)
	v_cvt_pk_bf16_f32 v3, v14, v15
	v_lshlrev_b64 v[6:7], 13, v[6:7]
	ds_read_b32 v8, v54
	ds_read_b32 v9, v54 offset:1028
	ds_read_b32 v10, v54 offset:2056
	ds_read_b32 v11, v54 offset:3084
	ds_read_b32 v12, v54 offset:4112
	ds_read_b32 v13, v54 offset:5140
	ds_read_b32 v14, v54 offset:6168
	ds_read_b32 v15, v54 offset:7196
	v_lshl_add_u64 v[6:7], v[4:5], 0, v[6:7]
	global_store_dwordx4 v[6:7], v[0:3], off
	v_add_u32_e32 v6, s8, v53
	v_ashrrev_i32_e32 v7, 31, v6
	v_lshlrev_b64 v[6:7], 13, v[6:7]
	s_add_i32 s14, s14, s15
	s_add_i32 s16, s16, s17
	s_waitcnt lgkmcnt(6)
	v_cvt_pk_bf16_f32 v0, v8, v9
	s_waitcnt lgkmcnt(4)
	v_cvt_pk_bf16_f32 v1, v10, v11
	s_waitcnt lgkmcnt(2)
	v_cvt_pk_bf16_f32 v2, v12, v13
	s_waitcnt lgkmcnt(0)
	v_cvt_pk_bf16_f32 v3, v14, v15
	v_lshl_add_u64 v[4:5], v[4:5], 0, v[6:7]
	s_cmpk_lt_i32 s14, 0x840
	global_store_dwordx4 v[4:5], v[0:3], off
	s_cbranch_scc0 .LBB0_159
